# attention unit epilogue: gate loads also widened to 16 bytes per lane via v_permlane32_swap (4 loads + 4 stores per lane)
# speedup vs baseline: 1.0196x; 1.0022x over previous
.LBB0_1053:
	ds_bpermute_b32 v0, v146, v148
	s_lshl_b32 s68, s17, 7
	v_lshlrev_b32_e32 v10, 3, v132
	v_mov_b32_e32 v11, v4
	s_waitcnt lgkmcnt(0)
	v_add_f32_e32 v0, v148, v0
	v_div_scale_f32 v1, s[0:1], v0, v0, 1.0
	v_rcp_f32_e32 v2, v1
	s_add_i32 s0, s19, s18
	v_fma_f32 v3, -v1, v2, 1.0
	v_fmac_f32_e32 v2, v3, v2
	v_div_scale_f32 v3, vcc, 1.0, v0, 1.0
	v_mul_f32_e32 v5, v3, v2
	v_fma_f32 v6, -v1, v5, v3
	v_fmac_f32_e32 v5, v6, v2
	v_fma_f32 v1, -v1, v5, v3
	v_div_fmas_f32 v1, v1, v2, v5
	v_add_u32_e32 v2, s0, v133
	v_ashrrev_i32_e32 v3, 31, v2
	v_mov_b64_e32 v[6:7], s[26:27]
	v_mad_i64_i32 v[8:9], s[0:1], v2, s92, v[6:7]
	v_lshlrev_b64 v[2:3], 9, v[2:3]
	v_sub_co_u32_e32 v2, vcc, 0, v2
	v_lshl_add_u64 v[6:7], v[8:9], 0, s[68:69]
	s_nop 0
	v_subb_co_u32_e32 v3, vcc, 0, v3, vcc
	v_lshl_add_u64 v[2:3], v[8:9], 0, v[2:3]
	v_lshl_add_u64 v[12:13], v[6:7], 0, v[10:11]
	s_mov_b64 s[0:1], 0x4512600
	v_lshl_add_u64 v[2:3], v[2:3], 0, s[68:69]
	v_lshl_add_u64 v[6:7], v[12:13], 0, s[0:1]
	v_lshl_add_u64 v[8:9], v[2:3], 0, v[10:11]
	s_mov_b64 s[0:1], 0x6d12400
	v_lshl_add_u64 v[2:3], v[8:9], 0, s[0:1]
	v_div_fixup_f32 v0, v1, v0, 1.0
	v_lshlrev_b32_e32 v10, 3, v132
	v_mov_b32_e32 v11, v4
	v_lshl_add_u64 v[6:7], v[6:7], 0, v[10:11]
	v_lshl_add_u64 v[2:3], v[2:3], 0, v[10:11]
	global_load_dwordx4 v[150:153], v[6:7], off
	global_load_dwordx4 v[154:157], v[6:7], off offset:32
	global_load_dwordx4 v[158:161], v[6:7], off offset:64
	global_load_dwordx4 v[162:165], v[6:7], off offset:96
	s_waitcnt vmcnt(3)
	v_permlane32_swap_b32_e32 v150, v152
	v_permlane32_swap_b32_e32 v151, v153
	v_pk_mul_f32 v[12:13], v[32:33], v[0:1] op_sel_hi:[1,0]
	v_lshlrev_b32_e32 v14, 16, v150
	v_and_b32_e32 v15, 0xffff0000, v150
	v_pk_mul_f32 v[12:13], v[12:13], v[14:15]
	v_pk_mul_f32 v[8:9], v[34:35], v[0:1] op_sel_hi:[1,0]
	v_cvt_pk_bf16_f32 v166, v12, v13
	v_lshlrev_b32_e32 v14, 16, v151
	v_and_b32_e32 v15, 0xffff0000, v151
	v_pk_mul_f32 v[8:9], v[8:9], v[14:15]
	s_nop 0
	v_cvt_pk_bf16_f32 v167, v8, v9
	v_pk_mul_f32 v[12:13], v[36:37], v[0:1] op_sel_hi:[1,0]
	v_lshlrev_b32_e32 v14, 16, v152
	v_and_b32_e32 v15, 0xffff0000, v152
	v_pk_mul_f32 v[12:13], v[12:13], v[14:15]
	v_pk_mul_f32 v[8:9], v[38:39], v[0:1] op_sel_hi:[1,0]
	v_cvt_pk_bf16_f32 v168, v12, v13
	v_lshlrev_b32_e32 v14, 16, v153
	v_and_b32_e32 v15, 0xffff0000, v153
	v_pk_mul_f32 v[8:9], v[8:9], v[14:15]
	s_nop 0
	v_cvt_pk_bf16_f32 v169, v8, v9
	s_nop 1
	v_permlane32_swap_b32_e32 v166, v168
	v_permlane32_swap_b32_e32 v167, v169
	global_store_dwordx4 v[2:3], v[166:169], off
	s_waitcnt vmcnt(3)
	v_permlane32_swap_b32_e32 v154, v156
	v_permlane32_swap_b32_e32 v155, v157
	v_pk_mul_f32 v[12:13], v[40:41], v[0:1] op_sel_hi:[1,0]
	v_lshlrev_b32_e32 v14, 16, v154
	v_and_b32_e32 v15, 0xffff0000, v154
	v_pk_mul_f32 v[12:13], v[12:13], v[14:15]
	v_pk_mul_f32 v[8:9], v[42:43], v[0:1] op_sel_hi:[1,0]
	v_cvt_pk_bf16_f32 v170, v12, v13
	v_lshlrev_b32_e32 v14, 16, v155
	v_and_b32_e32 v15, 0xffff0000, v155
	v_pk_mul_f32 v[8:9], v[8:9], v[14:15]
	s_nop 0
	v_cvt_pk_bf16_f32 v171, v8, v9
	v_pk_mul_f32 v[12:13], v[44:45], v[0:1] op_sel_hi:[1,0]
	v_lshlrev_b32_e32 v14, 16, v156
	v_and_b32_e32 v15, 0xffff0000, v156
	v_pk_mul_f32 v[12:13], v[12:13], v[14:15]
	v_pk_mul_f32 v[8:9], v[46:47], v[0:1] op_sel_hi:[1,0]
	v_cvt_pk_bf16_f32 v172, v12, v13
	v_lshlrev_b32_e32 v14, 16, v157
	v_and_b32_e32 v15, 0xffff0000, v157
	v_pk_mul_f32 v[8:9], v[8:9], v[14:15]
	s_nop 0
	v_cvt_pk_bf16_f32 v173, v8, v9
	s_nop 1
	v_permlane32_swap_b32_e32 v170, v172
	v_permlane32_swap_b32_e32 v171, v173
	global_store_dwordx4 v[2:3], v[170:173], off offset:32
	s_waitcnt vmcnt(3)
	v_permlane32_swap_b32_e32 v158, v160
	v_permlane32_swap_b32_e32 v159, v161
	v_pk_mul_f32 v[12:13], v[16:17], v[0:1] op_sel_hi:[1,0]
	v_lshlrev_b32_e32 v14, 16, v158
	v_and_b32_e32 v15, 0xffff0000, v158
	v_pk_mul_f32 v[12:13], v[12:13], v[14:15]
	v_pk_mul_f32 v[8:9], v[18:19], v[0:1] op_sel_hi:[1,0]
	v_cvt_pk_bf16_f32 v174, v12, v13
	v_lshlrev_b32_e32 v14, 16, v159
	v_and_b32_e32 v15, 0xffff0000, v159
	v_pk_mul_f32 v[8:9], v[8:9], v[14:15]
	s_nop 0
	v_cvt_pk_bf16_f32 v175, v8, v9
	v_pk_mul_f32 v[12:13], v[20:21], v[0:1] op_sel_hi:[1,0]
	v_lshlrev_b32_e32 v14, 16, v160
	v_and_b32_e32 v15, 0xffff0000, v160
	v_pk_mul_f32 v[12:13], v[12:13], v[14:15]
	v_pk_mul_f32 v[8:9], v[22:23], v[0:1] op_sel_hi:[1,0]
	v_cvt_pk_bf16_f32 v176, v12, v13
	v_lshlrev_b32_e32 v14, 16, v161
	v_and_b32_e32 v15, 0xffff0000, v161
	v_pk_mul_f32 v[8:9], v[8:9], v[14:15]
	s_nop 0
	v_cvt_pk_bf16_f32 v177, v8, v9
	s_nop 1
	v_permlane32_swap_b32_e32 v174, v176
	v_permlane32_swap_b32_e32 v175, v177
	global_store_dwordx4 v[2:3], v[174:177], off offset:64
	s_waitcnt vmcnt(3)
	v_permlane32_swap_b32_e32 v162, v164
	v_permlane32_swap_b32_e32 v163, v165
	v_pk_mul_f32 v[12:13], v[24:25], v[0:1] op_sel_hi:[1,0]
	v_lshlrev_b32_e32 v14, 16, v162
	v_and_b32_e32 v15, 0xffff0000, v162
	v_pk_mul_f32 v[12:13], v[12:13], v[14:15]
	v_pk_mul_f32 v[8:9], v[26:27], v[0:1] op_sel_hi:[1,0]
	v_cvt_pk_bf16_f32 v178, v12, v13
	v_lshlrev_b32_e32 v14, 16, v163
	v_and_b32_e32 v15, 0xffff0000, v163
	v_pk_mul_f32 v[8:9], v[8:9], v[14:15]
	s_nop 0
	v_cvt_pk_bf16_f32 v179, v8, v9
	v_pk_mul_f32 v[12:13], v[28:29], v[0:1] op_sel_hi:[1,0]
	v_lshlrev_b32_e32 v14, 16, v164
	v_and_b32_e32 v15, 0xffff0000, v164
	v_pk_mul_f32 v[12:13], v[12:13], v[14:15]
	v_pk_mul_f32 v[8:9], v[30:31], v[0:1] op_sel_hi:[1,0]
	v_cvt_pk_bf16_f32 v180, v12, v13
	v_lshlrev_b32_e32 v14, 16, v165
	v_and_b32_e32 v15, 0xffff0000, v165
	v_pk_mul_f32 v[8:9], v[8:9], v[14:15]
	s_nop 0
	v_cvt_pk_bf16_f32 v181, v8, v9
	s_nop 1
	v_permlane32_swap_b32_e32 v178, v180
	v_permlane32_swap_b32_e32 v179, v181
	global_store_dwordx4 v[2:3], v[178:181], off offset:96
